# mixer0 MFMA epilogue: the 8 u-value loads per lane issued together before the last MFMAs (counted waits) instead of 8 serialized load+wait round trips
# speedup vs baseline: 1.0005x; 1.0005x over previous
; #define LAS __attribute__((address_space(3)))
; __device__ __forceinline__ unsigned f2bf(float f) { unsigned u = __builtin_bit_cast(unsigned, f); return (u + 0x7fffu + ((u >> 16) & 1u)) >> 16; }
; __device__ __forceinline__ void mixer0_phase(KA a, lds8* lds, int tid, int lane, int wave) {
;     ...
;         for (int i = 0; i < 6; ++i) { const int row = rb + r0 - 1 + i; const bool ok = (row >= seqb) & (row < seqb + S);
;             if (ok) { cgv[i] = *(const u32x4*)(HB0 + (size_t)row * NIN + 3072 + h * 128 + cpc); xpv[i] = *(const u32x4*)(HB0 + (size_t)row * NIN + 4096 + h * 128 + cpc); }
;             else { cgv[i] = (u32x4){0u, 0u, 0u, 0u}; xpv[i] = (u32x4){0u, 0u, 0u, 0u}; } }
; #pragma unroll
;         for (int i = 0; i < 4; ++i) bgv[i] = *(const u32x4*)(HB0 + (size_t)(rb + r0 + i) * NIN + 2048 + h * 128 + cpc);
; #pragma unroll
;         for (int i = 0; i < 4; ++i) { const int p = tid + 512 * i, q = p >> 4, c0 = 8 * (p & 15);
;             float mean, rstd; st_mean_rstd(vs[i], 1.0f / 1024.0f, mean, rstd);
;             const f32x4 g0 = *(const f32x4*)(lng + h * 128 + c0), g1 = *(const f32x4*)(lng + h * 128 + c0 + 4), b0 = *(const f32x4*)(lnb + h * 128 + c0), b1 = *(const f32x4*)(lnb + h * 128 + c0 + 4);
; #pragma unroll
;             for (int j = 0; j < 4; ++j) { const float ga = j < 2 ? g0[2 * j] : g1[2 * j - 4], gb = j < 2 ? g0[2 * j + 1] : g1[2 * j - 3], ba = j < 2 ? b0[2 * j] : b1[2 * j - 4], bb = j < 2 ? b0[2 * j + 1] : b1[2 * j - 3];
;                 const float xa = (bflo(vw[i][j]) - mean) * rstd * ga + ba, xb2 = (bfhi(vw[i][j]) - mean) * rstd * gb + bb;
;                 const int ca = c0 + 2 * j, cb = ca + 1; const int swa = (ca & 15) ^ ((ca >> 4) & 7), swb = (cb & 15) ^ ((cb >> 4) & 7);
;                 *(LAS bf16_t*)(lds + ca * 256 + (((q >> 3) ^ swa) << 4) + (q & 7) * 2) = (bf16_t)f2bf(xa);
;                 *(LAS bf16_t*)(lds + cb * 256 + (((q >> 3) ^ swb) << 4) + (q & 7) * 2) = (bf16_t)f2bf(xb2); } }
.LBB0_486:
	s_or_b64 exec, exec, s[4:5]
	v_mov_b64_e32 v[136:137], s[6:7]
	v_mad_i64_i32 v[40:41], s[4:5], v130, s26, v[136:137]
	s_lshl_b32 s4, s41, 2
	s_mov_b32 s5, s17
	v_lshl_add_u64 v[42:43], v[116:117], 0, s[4:5]
	global_load_dwordx4 v[100:103], v[42:43], off offset:16
	global_load_dwordx4 v[108:111], v[42:43], off
	v_lshl_add_u64 v[42:43], v[118:119], 0, s[4:5]
	global_load_dwordx4 v[96:99], v[42:43], off offset:16
	global_load_dwordx4 v[104:107], v[42:43], off
	s_lshl_b32 s16, s41, 1
	v_lshl_add_u64 v[40:41], v[40:41], 0, s[16:17]
	v_or_b32_e32 v134, 1, v130
	v_lshl_add_u64 v[40:41], v[40:41], 0, v[114:115]
	v_mad_i64_i32 v[42:43], s[4:5], v134, s26, v[136:137]
	v_add_co_u32_e32 v40, vcc, s27, v40
	v_lshl_add_u64 v[42:43], v[42:43], 0, s[16:17]
	s_nop 0
	v_addc_co_u32_e32 v41, vcc, 0, v41, vcc
	v_lshl_add_u64 v[42:43], v[42:43], 0, v[114:115]
	v_add_co_u32_e32 v42, vcc, s27, v42
	v_or_b32_e32 v132, 2, v130
	s_nop 0
	v_addc_co_u32_e32 v43, vcc, 0, v43, vcc
	global_load_dwordx4 v[68:71], v[40:41], off
	global_load_dwordx4 v[64:67], v[42:43], off
	s_waitcnt vmcnt(12)
	v_cvt_f64_i32_e32 v[42:43], v29
	v_ldexp_f64 v[42:43], v[42:43], 32
	v_cvt_f64_u32_e32 v[28:29], v28
	v_add_f64 v[28:29], v[42:43], v[28:29]
	v_ldexp_f64 v[28:29], v[28:29], s29
	v_cvt_f32_f64_e32 v129, v[28:29]
	v_cvt_f64_i32_e32 v[28:29], v31
	v_ldexp_f64 v[28:29], v[28:29], 32
	v_cvt_f64_u32_e32 v[30:31], v30
	v_add_f64 v[28:29], v[28:29], v[30:31]
	v_ldexp_f64 v[28:29], v[28:29], s29
	v_mad_i64_i32 v[40:41], s[4:5], v132, s26, v[136:137]
	v_cvt_f32_f64_e32 v28, v[28:29]
	v_mul_f32_e32 v29, 0x3a800000, v129
	v_lshl_add_u64 v[40:41], v[40:41], 0, s[16:17]
	v_mul_f32_e32 v29, v29, v29
	v_lshl_add_u64 v[40:41], v[40:41], 0, v[114:115]
	v_fma_f32 v28, v28, s30, -v29
	v_add_co_u32_e32 v40, vcc, s27, v40
	v_max_f32_e32 v28, 0, v28
	s_nop 0
	v_addc_co_u32_e32 v41, vcc, 0, v41, vcc
	v_add_f32_e32 v28, 0x3727c5ac, v28
	v_mul_f32_e32 v29, 0x4f800000, v28
	v_cmp_gt_f32_e32 vcc, s31, v28
	v_or_b32_e32 v128, 3, v130
	v_add_u32_e32 v210, s42, v120
	v_cndmask_b32_e32 v30, v28, v29, vcc
	v_sqrt_f32_e32 v31, v30
	v_mad_i64_i32 v[28:29], s[4:5], v128, s26, v[136:137]
	v_lshl_add_u64 v[28:29], v[28:29], 0, s[16:17]
	v_add_u32_e32 v42, -1, v31
	v_fma_f32 v43, -v42, v31, v30
	v_cmp_ge_f32_e64 s[4:5], 0, v43
	v_add_u32_e32 v43, 1, v31
	v_lshl_add_u64 v[28:29], v[28:29], 0, v[114:115]
	v_cndmask_b32_e64 v42, v31, v42, s[4:5]
	v_fma_f32 v31, -v43, v31, v30
	v_cmp_lt_f32_e64 s[4:5], 0, v31
	v_ashrrev_i32_e32 v211, 31, v210
	s_waitcnt vmcnt(7)
	v_lshlrev_b32_e32 v218, 16, v39
	v_cndmask_b32_e64 v31, v42, v43, s[4:5]
	v_mul_f32_e32 v42, 0x37800000, v31
	v_cndmask_b32_e32 v31, v31, v42, vcc
	v_cmp_class_f32_e32 vcc, v30, v148
	v_lshlrev_b32_e32 v219, 16, v51
	s_waitcnt vmcnt(6)
	v_lshlrev_b32_e32 v220, 16, v35
	v_cndmask_b32_e32 v30, v31, v30, vcc
	v_div_scale_f32 v31, s[4:5], v30, v30, 1.0
	v_rcp_f32_e32 v131, v31
	v_add_co_u32_e32 v28, vcc, s27, v28
	v_lshlrev_b32_e32 v221, 16, v47
	s_nop 0
	v_addc_co_u32_e32 v29, vcc, 0, v29, vcc
	global_load_dwordx4 v[52:55], v[40:41], off
	s_nop 0
	global_load_dwordx4 v[40:43], v[28:29], off
	v_fma_f32 v28, -v31, v131, 1.0
	v_fmac_f32_e32 v131, v28, v131
	v_div_scale_f32 v28, vcc, 1.0, v30, 1.0
	v_mul_f32_e32 v29, v28, v131
	v_fma_f32 v133, -v31, v29, v28
	v_fmac_f32_e32 v29, v133, v131
	v_fma_f32 v28, -v31, v29, v28
	v_div_fmas_f32 v28, v28, v131, v29
	v_lshlrev_b32_e32 v29, 16, v24
	v_div_fixup_f32 v28, v28, v30, 1.0
	v_fmac_f32_e32 v29, 0xba800000, v129
	v_mul_f32_e32 v29, v29, v28
	v_and_b32_e32 v24, 0xffff0000, v24
	s_waitcnt vmcnt(4)
	v_fma_f32 v29, v29, v108, v104
	v_fmac_f32_e32 v24, 0xba800000, v129
	v_mul_f32_e32 v24, v24, v28
	v_bfe_u32 v30, v29, 16, 1
	v_fma_f32 v24, v24, v109, v105
	v_add3_u32 v29, v29, v30, s33
	ds_write_b16_d16_hi v149, v29
	v_bfe_u32 v29, v24, 16, 1
	v_add3_u32 v24, v24, v29, s33
	ds_write_b16_d16_hi v150, v24
	v_lshlrev_b32_e32 v24, 16, v25
	v_fmac_f32_e32 v24, 0xba800000, v129
	v_mul_f32_e32 v24, v24, v28
	v_and_b32_e32 v25, 0xffff0000, v25
	v_fma_f32 v24, v24, v110, v106
	v_fmac_f32_e32 v25, 0xba800000, v129
	v_mul_f32_e32 v25, v25, v28
	v_bfe_u32 v29, v24, 16, 1
	v_fma_f32 v25, v25, v111, v107
	v_add3_u32 v24, v24, v29, s33
	ds_write_b16_d16_hi v151, v24
	v_bfe_u32 v24, v25, 16, 1
	v_add3_u32 v24, v25, v24, s33
	ds_write_b16_d16_hi v152, v24
	v_lshlrev_b32_e32 v24, 16, v26
	v_fmac_f32_e32 v24, 0xba800000, v129
	v_mul_f32_e32 v24, v24, v28
	v_and_b32_e32 v25, 0xffff0000, v26
	v_fma_f32 v24, v24, v100, v96
	v_fmac_f32_e32 v25, 0xba800000, v129
	v_mul_f32_e32 v25, v25, v28
	v_bfe_u32 v26, v24, 16, 1
	v_fma_f32 v25, v25, v101, v97
	v_add3_u32 v24, v24, v26, s33
	ds_write_b16_d16_hi v153, v24
	v_bfe_u32 v24, v25, 16, 1
	v_add3_u32 v24, v25, v24, s33
	ds_write_b16_d16_hi v154, v24
	v_lshlrev_b32_e32 v24, 16, v27
	v_fmac_f32_e32 v24, 0xba800000, v129
	v_mul_f32_e32 v24, v24, v28
	v_fma_f32 v26, v24, v102, v98
	v_and_b32_e32 v24, 0xffff0000, v27
	v_fmac_f32_e32 v24, 0xba800000, v129
	v_mul_f32_e32 v24, v24, v28
	v_fma_f32 v27, v24, v103, v99
	v_cvt_f64_i32_e32 v[24:25], v21
	v_ldexp_f64 v[24:25], v[24:25], 32
	v_cvt_f64_u32_e32 v[20:21], v20
	v_add_f64 v[20:21], v[24:25], v[20:21]
	v_ldexp_f64 v[20:21], v[20:21], s29
	v_cvt_f32_f64_e32 v24, v[20:21]
	v_cvt_f64_i32_e32 v[20:21], v23
	v_ldexp_f64 v[20:21], v[20:21], 32
	v_cvt_f64_u32_e32 v[22:23], v22
	v_add_f64 v[20:21], v[20:21], v[22:23]
	v_ldexp_f64 v[20:21], v[20:21], s29
	v_cvt_f32_f64_e32 v20, v[20:21]
	v_mul_f32_e32 v21, 0x3a800000, v24
	v_mul_f32_e32 v21, v21, v21
	v_fma_f32 v20, v20, s30, -v21
	v_max_f32_e32 v20, 0, v20
	v_add_f32_e32 v20, 0x3727c5ac, v20
	v_mul_f32_e32 v21, 0x4f800000, v20
	v_cmp_gt_f32_e32 vcc, s31, v20
	v_bfe_u32 v22, v26, 16, 1
	v_add3_u32 v22, v26, v22, s33
	v_cndmask_b32_e32 v20, v20, v21, vcc
	v_sqrt_f32_e32 v21, v20
	ds_write_b16_d16_hi v155, v22
	v_ashrrev_i32_e32 v131, 31, v130
	v_and_b32_e32 v51, 0xffff0000, v51
	v_add_u32_e32 v22, -1, v21
	v_fma_f32 v23, -v22, v21, v20
	v_cmp_ge_f32_e64 s[4:5], 0, v23
	v_add_u32_e32 v23, 1, v21
	v_ashrrev_i32_e32 v135, 31, v134
	v_cndmask_b32_e64 v22, v21, v22, s[4:5]
	v_fma_f32 v21, -v23, v21, v20
	v_cmp_lt_f32_e64 s[4:5], 0, v21
	v_lshlrev_b64 v[130:131], 12, v[130:131]
	s_waitcnt vmcnt(3)
; #define LAS __attribute__((address_space(3)))
; __device__ __forceinline__ unsigned f2bf(float f) { unsigned u = __builtin_bit_cast(unsigned, f); return (u + 0x7fffu + ((u >> 16) & 1u)) >> 16; }
; __device__ __forceinline__ void mixer0_phase(KA a, lds8* lds, int tid, int lane, int wave) {
;     ...
;         for (int i = 0; i < 4; ++i) { const int p = tid + 512 * i, q = p >> 4, c0 = 8 * (p & 15);
;             float mean, rstd; st_mean_rstd(vs[i], 1.0f / 1024.0f, mean, rstd);
;             const f32x4 g0 = *(const f32x4*)(lng + h * 128 + c0), g1 = *(const f32x4*)(lng + h * 128 + c0 + 4), b0 = *(const f32x4*)(lnb + h * 128 + c0), b1 = *(const f32x4*)(lnb + h * 128 + c0 + 4);
; #pragma unroll
;             for (int j = 0; j < 4; ++j) { const float ga = j < 2 ? g0[2 * j] : g1[2 * j - 4], gb = j < 2 ? g0[2 * j + 1] : g1[2 * j - 3], ba = j < 2 ? b0[2 * j] : b1[2 * j - 4], bb = j < 2 ? b0[2 * j + 1] : b1[2 * j - 3];
;                 const float xa = (bflo(vw[i][j]) - mean) * rstd * ga + ba, xb2 = (bfhi(vw[i][j]) - mean) * rstd * gb + bb;
;                 const int ca = c0 + 2 * j, cb = ca + 1; const int swa = (ca & 15) ^ ((ca >> 4) & 7), swb = (cb & 15) ^ ((cb >> 4) & 7);
;                 *(LAS bf16_t*)(lds + ca * 256 + (((q >> 3) ^ swa) << 4) + (q & 7) * 2) = (bf16_t)f2bf(xa);
;                 *(LAS bf16_t*)(lds + cb * 256 + (((q >> 3) ^ swb) << 4) + (q & 7) * 2) = (bf16_t)f2bf(xb2); } }
	v_lshlrev_b32_e32 v197, 16, v68
	v_cndmask_b32_e64 v21, v22, v23, s[4:5]
	v_mul_f32_e32 v22, 0x37800000, v21
	v_cndmask_b32_e32 v21, v21, v22, vcc
	v_cmp_class_f32_e32 vcc, v20, v148
	v_bfe_u32 v23, v27, 16, 1
	v_add3_u32 v23, v27, v23, s33
	v_cndmask_b32_e32 v20, v21, v20, vcc
	v_div_scale_f32 v21, s[4:5], v20, v20, 1.0
	v_rcp_f32_e32 v22, v21
	ds_write_b16_d16_hi v156, v23
	v_ashrrev_i32_e32 v133, 31, v132
	v_fma_f32 v23, -v21, v22, 1.0
	v_fmac_f32_e32 v22, v23, v22
	v_div_scale_f32 v23, vcc, 1.0, v20, 1.0
	v_mul_f32_e32 v25, v23, v22
	v_fma_f32 v26, -v21, v25, v23
	v_fmac_f32_e32 v25, v26, v22
	v_fma_f32 v21, -v21, v25, v23
	v_div_fmas_f32 v21, v21, v22, v25
	v_div_fixup_f32 v20, v21, v20, 1.0
	v_lshlrev_b32_e32 v21, 16, v16
	v_fmac_f32_e32 v21, 0xba800000, v24
	v_mul_f32_e32 v21, v21, v20
	v_and_b32_e32 v16, 0xffff0000, v16
	v_fma_f32 v21, v21, v108, v104
	v_fmac_f32_e32 v16, 0xba800000, v24
	v_mul_f32_e32 v16, v16, v20
	v_bfe_u32 v22, v21, 16, 1
	v_fma_f32 v16, v16, v109, v105
	v_add3_u32 v21, v21, v22, s33
	ds_write_b16_d16_hi v157, v21
	v_bfe_u32 v21, v16, 16, 1
	v_add3_u32 v16, v16, v21, s33
	ds_write_b16_d16_hi v158, v16
	v_lshlrev_b32_e32 v16, 16, v17
	v_fmac_f32_e32 v16, 0xba800000, v24
	v_mul_f32_e32 v16, v16, v20
	v_and_b32_e32 v17, 0xffff0000, v17
	v_fma_f32 v16, v16, v110, v106
	v_fmac_f32_e32 v17, 0xba800000, v24
	v_mul_f32_e32 v17, v17, v20
	v_bfe_u32 v21, v16, 16, 1
	v_fma_f32 v17, v17, v111, v107
	v_add3_u32 v16, v16, v21, s33
	ds_write_b16_d16_hi v159, v16
	v_bfe_u32 v16, v17, 16, 1
	v_add3_u32 v16, v17, v16, s33
	ds_write_b16_d16_hi v160, v16
	v_lshlrev_b32_e32 v16, 16, v18
	v_fmac_f32_e32 v16, 0xba800000, v24
	v_mul_f32_e32 v16, v16, v20
	v_and_b32_e32 v17, 0xffff0000, v18
	v_fma_f32 v16, v16, v100, v96
	v_fmac_f32_e32 v17, 0xba800000, v24
	v_mul_f32_e32 v17, v17, v20
	v_bfe_u32 v18, v16, 16, 1
	v_fma_f32 v17, v17, v101, v97
	v_add3_u32 v16, v16, v18, s33
	ds_write_b16_d16_hi v161, v16
	v_bfe_u32 v16, v17, 16, 1
	v_add3_u32 v16, v17, v16, s33
	ds_write_b16_d16_hi v162, v16
	v_lshlrev_b32_e32 v16, 16, v19
	v_fmac_f32_e32 v16, 0xba800000, v24
	v_mul_f32_e32 v16, v16, v20
	v_fma_f32 v18, v16, v102, v98
	v_and_b32_e32 v16, 0xffff0000, v19
	v_fmac_f32_e32 v16, 0xba800000, v24
	v_mul_f32_e32 v16, v16, v20
	v_fma_f32 v19, v16, v103, v99
	v_cvt_f64_i32_e32 v[16:17], v13
	v_ldexp_f64 v[16:17], v[16:17], 32
	v_cvt_f64_u32_e32 v[12:13], v12
	v_add_f64 v[12:13], v[16:17], v[12:13]
	v_ldexp_f64 v[12:13], v[12:13], s29
	v_cvt_f32_f64_e32 v16, v[12:13]
	v_cvt_f64_i32_e32 v[12:13], v15
	v_ldexp_f64 v[12:13], v[12:13], 32
	v_cvt_f64_u32_e32 v[14:15], v14
	v_add_f64 v[12:13], v[12:13], v[14:15]
	v_ldexp_f64 v[12:13], v[12:13], s29
	v_cvt_f32_f64_e32 v12, v[12:13]
	v_mul_f32_e32 v13, 0x3a800000, v16
	v_mul_f32_e32 v13, v13, v13
	v_fma_f32 v12, v12, s30, -v13
	v_max_f32_e32 v12, 0, v12
	v_add_f32_e32 v12, 0x3727c5ac, v12
	v_mul_f32_e32 v13, 0x4f800000, v12
	v_cmp_gt_f32_e32 vcc, s31, v12
	v_bfe_u32 v14, v18, 16, 1
	v_add3_u32 v14, v18, v14, s33
	v_cndmask_b32_e32 v12, v12, v13, vcc
	v_sqrt_f32_e32 v13, v12
	ds_write_b16_d16_hi v163, v14
	v_add_u32_e32 v14, -1, v13
	v_fma_f32 v15, -v14, v13, v12
	v_cmp_ge_f32_e64 s[4:5], 0, v15
	v_add_u32_e32 v15, 1, v13
	s_nop 0
	v_cndmask_b32_e64 v14, v13, v14, s[4:5]
	v_fma_f32 v13, -v15, v13, v12
	v_cmp_lt_f32_e64 s[4:5], 0, v13
	s_nop 1
	v_cndmask_b32_e64 v13, v14, v15, s[4:5]
	v_mul_f32_e32 v14, 0x37800000, v13
	v_cndmask_b32_e32 v13, v13, v14, vcc
	v_cmp_class_f32_e32 vcc, v12, v148
	v_bfe_u32 v15, v19, 16, 1
	v_add3_u32 v15, v19, v15, s33
	v_cndmask_b32_e32 v12, v13, v12, vcc
	v_div_scale_f32 v13, s[4:5], v12, v12, 1.0
	v_rcp_f32_e32 v14, v13
	ds_write_b16_d16_hi v164, v15
	v_fma_f32 v15, -v13, v14, 1.0
	v_fmac_f32_e32 v14, v15, v14
	v_div_scale_f32 v15, vcc, 1.0, v12, 1.0
	v_mul_f32_e32 v17, v15, v14
	v_fma_f32 v18, -v13, v17, v15
	v_fmac_f32_e32 v17, v18, v14
	v_fma_f32 v13, -v13, v17, v15
	v_div_fmas_f32 v13, v13, v14, v17
	v_div_fixup_f32 v12, v13, v12, 1.0
	v_lshlrev_b32_e32 v13, 16, v8
	v_fmac_f32_e32 v13, 0xba800000, v16
	v_mul_f32_e32 v13, v13, v12
	v_and_b32_e32 v8, 0xffff0000, v8
	v_fma_f32 v13, v13, v108, v104
	v_fmac_f32_e32 v8, 0xba800000, v16
	v_mul_f32_e32 v8, v8, v12
	v_bfe_u32 v14, v13, 16, 1
	v_fma_f32 v8, v8, v109, v105
	v_add3_u32 v13, v13, v14, s33
	ds_write_b16_d16_hi v165, v13
	v_bfe_u32 v13, v8, 16, 1
	v_add3_u32 v8, v8, v13, s33
	ds_write_b16_d16_hi v166, v8
	v_lshlrev_b32_e32 v8, 16, v9
	v_fmac_f32_e32 v8, 0xba800000, v16
	v_mul_f32_e32 v8, v8, v12
	v_and_b32_e32 v9, 0xffff0000, v9
	v_fma_f32 v8, v8, v110, v106
	v_fmac_f32_e32 v9, 0xba800000, v16
	v_mul_f32_e32 v9, v9, v12
	v_bfe_u32 v13, v8, 16, 1
	v_fma_f32 v9, v9, v111, v107
	v_add3_u32 v8, v8, v13, s33
	ds_write_b16_d16_hi v167, v8
	v_bfe_u32 v8, v9, 16, 1
	v_add3_u32 v8, v9, v8, s33
	ds_write_b16_d16_hi v168, v8
	v_lshlrev_b32_e32 v8, 16, v10
	v_fmac_f32_e32 v8, 0xba800000, v16
	v_mul_f32_e32 v8, v8, v12
	v_and_b32_e32 v9, 0xffff0000, v10
	v_fma_f32 v8, v8, v100, v96
	v_fmac_f32_e32 v9, 0xba800000, v16
	v_mul_f32_e32 v9, v9, v12
	v_bfe_u32 v10, v8, 16, 1
	v_fma_f32 v9, v9, v101, v97
	v_add3_u32 v8, v8, v10, s33
	ds_write_b16_d16_hi v169, v8
	v_bfe_u32 v8, v9, 16, 1
	v_add3_u32 v8, v9, v8, s33
	ds_write_b16_d16_hi v170, v8
	v_lshlrev_b32_e32 v8, 16, v11
	v_fmac_f32_e32 v8, 0xba800000, v16
	v_mul_f32_e32 v8, v8, v12
	v_fma_f32 v10, v8, v102, v98
	v_and_b32_e32 v8, 0xffff0000, v11
	v_fmac_f32_e32 v8, 0xba800000, v16
	v_mul_f32_e32 v8, v8, v12
	v_fma_f32 v11, v8, v103, v99
	v_cvt_f64_i32_e32 v[8:9], v5
	v_ldexp_f64 v[8:9], v[8:9], 32
	v_cvt_f64_u32_e32 v[4:5], v4
	v_add_f64 v[4:5], v[8:9], v[4:5]
	v_ldexp_f64 v[4:5], v[4:5], s29
; __device__ __forceinline__ void mixer0_phase(KA a, lds8* lds, int tid, int lane, int wave) {
;     ...
;         for (int i = 0; i < 4; ++i) { const int p = tid + 512 * i, q = p >> 4, c0 = 8 * (p & 15);
;             float mean, rstd; st_mean_rstd(vs[i], 1.0f / 1024.0f, mean, rstd);
;             const f32x4 g0 = *(const f32x4*)(lng + h * 128 + c0), g1 = *(const f32x4*)(lng + h * 128 + c0 + 4), b0 = *(const f32x4*)(lnb + h * 128 + c0), b1 = *(const f32x4*)(lnb + h * 128 + c0 + 4);
; #pragma unroll
;             for (int j = 0; j < 4; ++j) { const float ga = j < 2 ? g0[2 * j] : g1[2 * j - 4], gb = j < 2 ? g0[2 * j + 1] : g1[2 * j - 3], ba = j < 2 ? b0[2 * j] : b1[2 * j - 4], bb = j < 2 ? b0[2 * j + 1] : b1[2 * j - 3];
;                 const float xa = (bflo(vw[i][j]) - mean) * rstd * ga + ba, xb2 = (bfhi(vw[i][j]) - mean) * rstd * gb + bb;
;                 const int ca = c0 + 2 * j, cb = ca + 1; const int swa = (ca & 15) ^ ((ca >> 4) & 7), swb = (cb & 15) ^ ((cb >> 4) & 7);
;                 *(LAS bf16_t*)(lds + ca * 256 + (((q >> 3) ^ swa) << 4) + (q & 7) * 2) = (bf16_t)f2bf(xa);
;                 *(LAS bf16_t*)(lds + cb * 256 + (((q >> 3) ^ swb) << 4) + (q & 7) * 2) = (bf16_t)f2bf(xb2); } }
;     ...
;         { const int pb = wave >> 1; f32x16 acc0, acc1;
; #pragma unroll
;           for (int r = 0; r < 16; ++r) { acc0[r] = 0.f; acc1[r] = 0.f; }
;           const bf16_t* wrow = SW + (size_t)h * 16384 + (size_t)(32 * pb + l31) * 128 + 8 * hh; const int cb0 = 2 * (wave & 1);
;           const int ca = 32 * cb0 + l31, cc = ca + 32; const int swa = (ca & 15) ^ ((ca >> 4) & 7), swc = (cc & 15) ^ ((cc >> 4) & 7);
; #pragma unroll
;           for (int ks = 0; ks < 8; ++ks) { const bf16x8 bw = *(const bf16x8*)(wrow + 16 * ks);
;               const bf16x8 a0 = *(const LAS bf16x8*)(lds + ca * 256 + (((2 * ks + hh) ^ swa) << 4)), a1 = *(const LAS bf16x8*)(lds + cc * 256 + (((2 * ks + hh) ^ swc) << 4));
;               acc0 = MFMA32(a0, bw, acc0); acc1 = MFMA32(a1, bw, acc1); }
;           const int p = 32 * pb + l31; const float bsv = sb[h * 128 + p]; const size_t rowo = (size_t)(rb + p);
; #pragma unroll
;           for (int t = 0; t < 2; ++t) { const f32x16& ac = t ? acc1 : acc0;
; #pragma unroll
;               for (int r4 = 0; r4 < 4; ++r4) { const int c = 32 * (cb0 + t) + 8 * r4 + 4 * hh; const u32x2 uu = *(const u32x2*)(HB0 + rowo * NIN + h * 128 + c);
	v_cvt_f32_f64_e32 v8, v[4:5]
	v_cvt_f64_i32_e32 v[4:5], v7
	v_ldexp_f64 v[4:5], v[4:5], 32
	v_cvt_f64_u32_e32 v[6:7], v6
	v_add_f64 v[4:5], v[4:5], v[6:7]
	v_ldexp_f64 v[4:5], v[4:5], s29
	v_cvt_f32_f64_e32 v4, v[4:5]
	v_mul_f32_e32 v5, 0x3a800000, v8
	v_mul_f32_e32 v5, v5, v5
	v_fma_f32 v4, v4, s30, -v5
	v_max_f32_e32 v4, 0, v4
	v_add_f32_e32 v4, 0x3727c5ac, v4
	v_mul_f32_e32 v5, 0x4f800000, v4
	v_cmp_gt_f32_e32 vcc, s31, v4
	v_bfe_u32 v6, v10, 16, 1
	v_add3_u32 v6, v10, v6, s33
	v_cndmask_b32_e32 v4, v4, v5, vcc
	v_sqrt_f32_e32 v5, v4
	ds_write_b16_d16_hi v171, v6
	v_add_u32_e32 v6, -1, v5
	v_fma_f32 v7, -v6, v5, v4
	v_cmp_ge_f32_e64 s[4:5], 0, v7
	v_add_u32_e32 v7, 1, v5
	s_nop 0
	v_cndmask_b32_e64 v6, v5, v6, s[4:5]
	v_fma_f32 v5, -v7, v5, v4
	v_cmp_lt_f32_e64 s[4:5], 0, v5
	s_nop 1
	v_cndmask_b32_e64 v5, v6, v7, s[4:5]
	v_mul_f32_e32 v6, 0x37800000, v5
	v_cndmask_b32_e32 v5, v5, v6, vcc
	v_cmp_class_f32_e32 vcc, v4, v148
	v_bfe_u32 v7, v11, 16, 1
	v_add3_u32 v7, v11, v7, s33
	v_cndmask_b32_e32 v4, v5, v4, vcc
	v_div_scale_f32 v5, s[4:5], v4, v4, 1.0
	v_rcp_f32_e32 v6, v5
	ds_write_b16_d16_hi v172, v7
	s_lshl_b32 s4, s43, 15
	s_mov_b32 s5, s17
	v_fma_f32 v7, -v5, v6, 1.0
	v_fmac_f32_e32 v6, v7, v6
	v_div_scale_f32 v7, vcc, 1.0, v4, 1.0
	v_mul_f32_e32 v9, v7, v6
	v_fma_f32 v10, -v5, v9, v7
	v_fmac_f32_e32 v9, v10, v6
	v_fma_f32 v5, -v5, v9, v7
	v_div_fmas_f32 v5, v5, v6, v9
	v_div_fixup_f32 v4, v5, v4, 1.0
	v_lshlrev_b32_e32 v5, 16, v0
	v_fmac_f32_e32 v5, 0xba800000, v8
	v_mul_f32_e32 v5, v5, v4
	v_and_b32_e32 v0, 0xffff0000, v0
	v_fma_f32 v5, v5, v108, v104
	v_fmac_f32_e32 v0, 0xba800000, v8
	v_mul_f32_e32 v0, v0, v4
	v_bfe_u32 v6, v5, 16, 1
	v_fma_f32 v0, v0, v109, v105
	v_add3_u32 v5, v5, v6, s33
	ds_write_b16_d16_hi v173, v5
	v_bfe_u32 v5, v0, 16, 1
	v_add3_u32 v0, v0, v5, s33
	ds_write_b16_d16_hi v174, v0
	v_lshlrev_b32_e32 v0, 16, v1
	v_fmac_f32_e32 v0, 0xba800000, v8
	v_and_b32_e32 v1, 0xffff0000, v1
	v_mul_f32_e32 v0, v0, v4
	v_fmac_f32_e32 v1, 0xba800000, v8
	v_fma_f32 v0, v0, v110, v106
	v_mul_f32_e32 v1, v1, v4
	v_fmac_f32_e32 v107, v1, v111
	v_bfe_u32 v1, v0, 16, 1
	v_add3_u32 v0, v0, v1, s33
	ds_write_b16_d16_hi v175, v0
	v_bfe_u32 v0, v107, 16, 1
	v_add3_u32 v0, v107, v0, s33
	ds_write_b16_d16_hi v176, v0
	v_lshlrev_b32_e32 v0, 16, v2
	v_fmac_f32_e32 v0, 0xba800000, v8
	v_mul_f32_e32 v0, v0, v4
	v_and_b32_e32 v1, 0xffff0000, v2
	v_fma_f32 v0, v0, v100, v96
	v_fmac_f32_e32 v1, 0xba800000, v8
	v_mul_f32_e32 v1, v1, v4
	v_bfe_u32 v2, v0, 16, 1
	v_fma_f32 v1, v1, v101, v97
	v_add3_u32 v0, v0, v2, s33
	ds_write_b16_d16_hi v177, v0
	v_bfe_u32 v0, v1, 16, 1
	v_add3_u32 v0, v1, v0, s33
	ds_write_b16_d16_hi v178, v0
	v_lshlrev_b32_e32 v0, 16, v3
	v_fmac_f32_e32 v0, 0xba800000, v8
	v_and_b32_e32 v1, 0xffff0000, v3
	v_mul_f32_e32 v0, v0, v4
	v_fmac_f32_e32 v1, 0xba800000, v8
	v_fma_f32 v0, v0, v102, v98
	v_mul_f32_e32 v1, v1, v4
	v_fmac_f32_e32 v99, v1, v103
	v_bfe_u32 v1, v0, 16, 1
	v_add3_u32 v0, v0, v1, s33
	ds_write_b16_d16_hi v179, v0
	v_bfe_u32 v0, v99, 16, 1
	v_add3_u32 v0, v99, v0, s33
	v_lshl_add_u64 v[142:143], v[122:123], 0, s[4:5]
	ds_write_b16_d16_hi v180, v0
	s_waitcnt lgkmcnt(0)
	s_barrier
	global_load_dwordx4 v[0:3], v[142:143], off
	global_load_dwordx4 v[96:99], v[142:143], off offset:32
	ds_read_b128 v[4:7], v181
	ds_read_b128 v[8:11], v182
	global_load_dwordx4 v[100:103], v[142:143], off offset:64
	s_waitcnt vmcnt(2) lgkmcnt(1)
	v_mfma_f32_32x32x16_bf16 v[16:31], v[4:7], v[0:3], 0
	ds_read_b128 v[104:107], v183
	ds_read_b128 v[108:111], v184
	v_mad_i64_i32 v[136:137], s[4:5], v210, s26, v[136:137]
	v_lshl_add_u64 v[212:213], v[136:137], 0, s[16:17]
	v_lshl_add_u64 v[214:215], v[212:213], 0, v[124:125]
	s_add_u32 s4, s12, s16
	s_addc_u32 s5, s13, 0
	s_waitcnt vmcnt(1) lgkmcnt(1)
	v_mfma_f32_32x32x16_bf16 v[16:31], v[104:107], v[96:99], v[16:31]
	global_load_dwordx4 v[104:107], v[142:143], off offset:96
	s_add_i32 s40, s40, s38
	s_add_i32 s24, s24, s25
	s_cmpk_lt_i32 s40, 0xc00
	v_mfma_f32_32x32x16_bf16 v[0:15], v[8:11], v[0:3], 0
	s_waitcnt lgkmcnt(0)
	v_mfma_f32_32x32x16_bf16 v[0:15], v[108:111], v[96:99], v[0:15]
	global_load_dwordx4 v[96:99], v[142:143], off offset:128
	ds_read_b128 v[108:111], v185
	ds_read_b128 v[138:141], v186
	ds_read_b128 v[198:201], v187
	s_waitcnt vmcnt(2) lgkmcnt(2)
	v_mfma_f32_32x32x16_bf16 v[16:31], v[108:111], v[100:103], v[16:31]
	global_load_dwordx4 v[108:111], v[142:143], off offset:160
	s_waitcnt lgkmcnt(1)
	v_mfma_f32_32x32x16_bf16 v[0:15], v[138:141], v[100:103], v[0:15]
	global_load_dwordx4 v[100:103], v[142:143], off offset:192
	ds_read_b128 v[138:141], v188
	s_waitcnt vmcnt(3) lgkmcnt(1)
	v_mfma_f32_32x32x16_bf16 v[16:31], v[198:201], v[104:107], v[16:31]
	global_load_dwordx4 v[198:201], v[142:143], off offset:224
	v_add_u32_e32 v142, s41, v120
	v_mov_b32_e32 v143, v115
	v_lshl_add_u64 v[142:143], v[142:143], 2, s[8:9]
	global_load_dwordx2 v[216:217], v[214:215], off
	global_load_dword v129, v[142:143], off
	global_load_dwordx2 v[222:223], v[214:215], off offset:16
	global_load_dwordx2 v[224:225], v[214:215], off offset:32
	global_load_dwordx2 v[226:227], v[214:215], off offset:48
	v_lshl_add_u64 v[236:237], v[212:213], 0, v[126:127]
	global_load_dwordx2 v[228:229], v[236:237], off offset:64
	global_load_dwordx2 v[230:231], v[236:237], off offset:80
	global_load_dwordx2 v[232:233], v[236:237], off offset:96
	global_load_dwordx2 v[234:235], v[236:237], off offset:112
	s_waitcnt lgkmcnt(0)
	v_mfma_f32_32x32x16_bf16 v[0:15], v[138:141], v[104:107], v[0:15]
	ds_read_b128 v[104:107], v189
	ds_read_b128 v[136:139], v190
	s_waitcnt vmcnt(12) lgkmcnt(1)
; #define LAS __attribute__((address_space(3)))
; #define MFMA32(a, b, c) __builtin_amdgcn_mfma_f32_32x32x16_bf16((a), (b), (c), 0, 0, 0)
; __device__ __forceinline__ unsigned pk2(float lo, float hi) { return cvt_pk_bf16(lo, hi); }
; __device__ __forceinline__ void mixer0_phase(KA a, lds8* lds, int tid, int lane, int wave) {
;     ...
;           for (int ks = 0; ks < 8; ++ks) { const bf16x8 bw = *(const bf16x8*)(wrow + 16 * ks);
;               const bf16x8 a0 = *(const LAS bf16x8*)(lds + ca * 256 + (((2 * ks + hh) ^ swa) << 4)), a1 = *(const LAS bf16x8*)(lds + cc * 256 + (((2 * ks + hh) ^ swc) << 4));
;               acc0 = MFMA32(a0, bw, acc0); acc1 = MFMA32(a1, bw, acc1); }
;           const int p = 32 * pb + l31; const float bsv = sb[h * 128 + p]; const size_t rowo = (size_t)(rb + p);
; #pragma unroll
;           for (int t = 0; t < 2; ++t) { const f32x16& ac = t ? acc1 : acc0;
; #pragma unroll
;               for (int r4 = 0; r4 < 4; ++r4) { const int c = 32 * (cb0 + t) + 8 * r4 + 4 * hh; const u32x2 uu = *(const u32x2*)(HB0 + rowo * NIN + h * 128 + c);
;                   const float y0 = bflo(uu.x) * (ac[4 * r4] + bsv), y1 = bfhi(uu.x) * (ac[4 * r4 + 1] + bsv), y2 = bflo(uu.y) * (ac[4 * r4 + 2] + bsv), y3 = bfhi(uu.y) * (ac[4 * r4 + 3] + bsv);
;                   u32x2 w; w.x = pk2(y0, y1); w.y = pk2(y2, y3); *(u32x2*)(YC + rowo * DM + h * 128 + c) = w; } } }
	v_mfma_f32_32x32x16_bf16 v[16:31], v[104:107], v[96:99], v[16:31]
	ds_read_b128 v[104:107], v191
	ds_read_b128 v[140:143], v192
	s_waitcnt vmcnt(11) lgkmcnt(1)
	v_mfma_f32_32x32x16_bf16 v[16:31], v[104:107], v[108:111], v[16:31]
	ds_read_b128 v[104:107], v193
	ds_read_b128 v[202:205], v194
	s_waitcnt vmcnt(10) lgkmcnt(1)
	v_mfma_f32_32x32x16_bf16 v[16:31], v[104:107], v[100:103], v[16:31]
	ds_read_b128 v[104:107], v195
	ds_read_b128 v[206:209], v196
	s_waitcnt vmcnt(9) lgkmcnt(1)
	v_mfma_f32_32x32x16_bf16 v[16:31], v[104:107], v[198:201], v[16:31]
	v_lshlrev_b32_e32 v106, 16, v63
	v_lshlrev_b32_e32 v107, 16, v83
	s_waitcnt vmcnt(8)
	v_lshlrev_b32_e32 v104, 16, v216
	v_lshlrev_b32_e32 v105, 16, v79
	s_waitcnt vmcnt(0)
	s_nop 5
	v_add_f32_e32 v16, v16, v129
	v_mul_f32_e32 v16, v16, v104
	v_and_b32_e32 v104, 0xffff0000, v216
	v_add_f32_e32 v17, v17, v129
	v_mul_f32_e32 v17, v17, v104
	v_lshlrev_b32_e32 v104, 16, v217
	v_add_f32_e32 v18, v18, v129
	v_mul_f32_e32 v18, v18, v104
	v_and_b32_e32 v104, 0xffff0000, v217
	v_add_f32_e32 v19, v19, v129
	v_mul_f32_e32 v19, v19, v104
	v_cvt_pk_bf16_f32 v16, v16, v17
	v_cvt_pk_bf16_f32 v17, v18, v19
	v_mfma_f32_32x32x16_bf16 v[0:15], v[136:139], v[96:99], v[0:15]
	v_lshlrev_b64 v[96:97], 12, v[210:211]
	v_lshl_add_u64 v[96:97], s[4:5], 0, v[96:97]
	v_lshl_add_u64 v[98:99], v[96:97], 0, v[124:125]
	global_store_dwordx2 v[98:99], v[16:17], off
	v_add_f32_e32 v17, v20, v129
	v_add_f32_e32 v20, v22, v129
	v_and_b32_e32 v210, 0xffff0000, v61
	v_mfma_f32_32x32x16_bf16 v[0:15], v[140:143], v[108:111], v[0:15]
	v_lshlrev_b32_e32 v138, 16, v62
	v_lshlrev_b32_e32 v140, 16, v58
	v_and_b32_e32 v108, 0xffff0000, v62
	v_and_b32_e32 v110, 0xffff0000, v58
	v_lshlrev_b32_e32 v104, 16, v59
	v_and_b32_e32 v211, 0xffff0000, v81
	v_lshlrev_b32_e32 v139, 16, v82
	v_mfma_f32_32x32x16_bf16 v[0:15], v[202:205], v[100:103], v[0:15]
	v_and_b32_e32 v202, 0xffff0000, v60
	v_and_b32_e32 v204, 0xffff0000, v56
	v_and_b32_e32 v100, 0xffff0000, v63
	v_and_b32_e32 v102, 0xffff0000, v59
	v_and_b32_e32 v203, 0xffff0000, v80
	v_and_b32_e32 v205, 0xffff0000, v76
	v_lshlrev_b32_e32 v141, 16, v78
	s_waitcnt lgkmcnt(0)
	v_mfma_f32_32x32x16_bf16 v[0:15], v[206:209], v[198:201], v[0:15]
	v_lshlrev_b32_e32 v198, 16, v60
	v_lshlrev_b32_e32 v200, 16, v56
	v_lshlrev_b32_e32 v206, 16, v57
	v_lshlrev_b32_e32 v208, 16, v61
	v_lshlrev_b32_e32 v199, 16, v80
	v_lshlrev_b32_e32 v201, 16, v76
	v_lshlrev_b32_e32 v209, 16, v81
	s_nop 4
	v_add_f32_e32 v1, v129, v1
	v_add_f32_e32 v2, v129, v2
	v_add_f32_e32 v0, v129, v0
	v_add_f32_e32 v3, v129, v3
	v_add_f32_e32 v4, v129, v4
	v_add_f32_e32 v5, v129, v5
	v_add_f32_e32 v6, v129, v6
	v_add_f32_e32 v7, v129, v7
	v_lshlrev_b32_e32 v207, 16, v77
	v_and_b32_e32 v109, 0xffff0000, v82
	v_and_b32_e32 v111, 0xffff0000, v78
	v_and_b32_e32 v101, 0xffff0000, v83
	v_and_b32_e32 v103, 0xffff0000, v79
	v_and_b32_e32 v82, 0xffff0000, v84
	v_lshlrev_b32_e32 v78, 16, v73
	v_lshlrev_b32_e32 v80, 16, v85
	v_and_b32_e32 v76, 0xffff0000, v73
	v_lshlrev_b32_e32 v60, 16, v86
	v_lshlrev_b32_e32 v62, 16, v74
	v_and_b32_e32 v56, 0xffff0000, v86
	v_and_b32_e32 v58, 0xffff0000, v74
	v_and_b32_e32 v83, 0xffff0000, v92
	v_lshlrev_b32_e32 v81, 16, v93
	v_lshlrev_b32_e32 v79, 16, v89
	v_and_b32_e32 v73, 0xffff0000, v93
	v_lshlrev_b32_e32 v61, 16, v94
	v_lshlrev_b32_e32 v63, 16, v90
	v_and_b32_e32 v59, 0xffff0000, v90
	v_lshlrev_b32_e32 v74, 16, v36
	v_lshlrev_b32_e32 v86, 16, v32
	v_and_b32_e32 v90, 0xffff0000, v32
	v_lshlrev_b32_e32 v93, 16, v49
	v_and_b32_e32 v49, 0xffff0000, v49
	v_lshlrev_b32_e32 v32, 16, v38
	v_and_b32_e32 v217, 0xffff0000, v46
	v_and_b32_e32 v216, 0xffff0000, v34
	v_lshlrev_b32_e32 v16, 16, v222
	v_mul_f32_e32 v16, v17, v16
	v_and_b32_e32 v17, 0xffff0000, v222
	v_add_f32_e32 v18, v21, v129
	v_mul_f32_e32 v17, v18, v17
	v_lshlrev_b32_e32 v18, 16, v223
	v_mul_f32_e32 v18, v20, v18
	v_and_b32_e32 v19, 0xffff0000, v223
	v_add_f32_e32 v20, v23, v129
	v_mul_f32_e32 v19, v20, v19
	v_cvt_pk_bf16_f32 v16, v16, v17
	v_cvt_pk_bf16_f32 v17, v18, v19
	v_add_f32_e32 v20, v26, v129
	global_store_dwordx2 v[98:99], v[16:17], off offset:16
	v_add_f32_e32 v17, v24, v129
	v_and_b32_e32 v24, 0xffff0000, v87
	v_and_b32_e32 v26, 0xffff0000, v75
	v_lshlrev_b32_e32 v16, 16, v224
	v_mul_f32_e32 v16, v17, v16
	v_and_b32_e32 v17, 0xffff0000, v224
	v_add_f32_e32 v18, v25, v129
	v_mul_f32_e32 v17, v18, v17
	v_lshlrev_b32_e32 v18, 16, v225
	v_mul_f32_e32 v18, v20, v18
	v_and_b32_e32 v19, 0xffff0000, v225
	v_add_f32_e32 v20, v27, v129
	v_mul_f32_e32 v19, v20, v19
	v_cvt_pk_bf16_f32 v16, v16, v17
	v_cvt_pk_bf16_f32 v17, v18, v19
	v_add_f32_e32 v20, v30, v129
	global_store_dwordx2 v[98:99], v[16:17], off offset:32
	v_add_f32_e32 v17, v28, v129
	v_lshlrev_b32_e32 v28, 16, v75
	v_lshlrev_b32_e32 v30, 16, v87
	v_and_b32_e32 v25, 0xffff0000, v95
	v_and_b32_e32 v27, 0xffff0000, v91
	v_lshlrev_b32_e32 v75, 16, v48
	v_lshlrev_b32_e32 v87, 16, v44
	v_and_b32_e32 v215, 0xffff0000, v50
	v_and_b32_e32 v214, 0xffff0000, v38
	v_and_b32_e32 v38, 0xffff0000, v35
	v_pk_mul_f32 v[142:143], v[86:87], v[74:75]
	v_pk_mul_f32 v[86:87], v[220:221], v[218:219]
	v_and_b32_e32 v218, 0xffff0000, v66
	v_lshlrev_b32_e32 v219, 16, v67
	v_and_b32_e32 v220, 0xffff0000, v67
	v_lshlrev_b32_e32 v16, 16, v226
	v_mul_f32_e32 v16, v17, v16
	v_and_b32_e32 v17, 0xffff0000, v226
	v_add_f32_e32 v18, v29, v129
	v_mul_f32_e32 v17, v18, v17
	v_lshlrev_b32_e32 v18, 16, v227
	v_mul_f32_e32 v18, v20, v18
	v_and_b32_e32 v19, 0xffff0000, v227
	v_add_f32_e32 v20, v31, v129
	v_mul_f32_e32 v19, v20, v19
	v_cvt_pk_bf16_f32 v16, v16, v17
	v_cvt_pk_bf16_f32 v17, v18, v19
	global_store_dwordx2 v[98:99], v[16:17], off offset:48
; __device__ __forceinline__ unsigned pk2(float lo, float hi) { return cvt_pk_bf16(lo, hi); }
; __device__ __forceinline__ void mixer0_phase(KA a, lds8* lds, int tid, int lane, int wave) {
;     ...
;           const int p = 32 * pb + l31; const float bsv = sb[h * 128 + p]; const size_t rowo = (size_t)(rb + p);
; #pragma unroll
;           for (int t = 0; t < 2; ++t) { const f32x16& ac = t ? acc1 : acc0;
; #pragma unroll
;               for (int r4 = 0; r4 < 4; ++r4) { const int c = 32 * (cb0 + t) + 8 * r4 + 4 * hh; const u32x2 uu = *(const u32x2*)(HB0 + rowo * NIN + h * 128 + c);
;                   const float y0 = bflo(uu.x) * (ac[4 * r4] + bsv), y1 = bfhi(uu.x) * (ac[4 * r4 + 1] + bsv), y2 = bflo(uu.y) * (ac[4 * r4 + 2] + bsv), y3 = bfhi(uu.y) * (ac[4 * r4 + 3] + bsv);
;                   u32x2 w; w.x = pk2(y0, y1); w.y = pk2(y2, y3); *(u32x2*)(YC + rowo * DM + h * 128 + c) = w; } } }
;         { float w0[8], w1[8], w2[8];
; #pragma unroll
;           for (int j = 0; j < 8; ++j) { w0[j] = cw[h * 128 + cpc + j]; w1[j] = cw[1024 + h * 128 + cpc + j]; w2[j] = cw[2048 + h * 128 + cpc + j]; }
;           float z[6][8];
; #pragma unroll
;           for (int i = 0; i < 6; ++i)
; #pragma unroll
;               for (int j = 0; j < 4; ++j) { z[i][2 * j] = bflo(cgv[i][j]) * bflo(xpv[i][j]); z[i][2 * j + 1] = bfhi(cgv[i][j]) * bfhi(xpv[i][j]); }
	v_lshl_add_u64 v[16:17], v[212:213], 0, v[126:127]
	v_and_b32_e32 v212, 0xffff0000, v57
	v_and_b32_e32 v213, 0xffff0000, v77
	v_lshlrev_b32_e32 v98, 16, v72
	v_lshlrev_b32_e32 v99, 16, v88
	v_and_b32_e32 v77, 0xffff0000, v89
	v_and_b32_e32 v57, 0xffff0000, v94
	v_lshlrev_b32_e32 v31, 16, v95
	v_lshlrev_b32_e32 v29, 16, v91
	v_and_b32_e32 v89, 0xffff0000, v48
	v_and_b32_e32 v91, 0xffff0000, v44
	v_lshlrev_b32_e32 v94, 16, v33
	v_lshlrev_b32_e32 v95, 16, v45
	v_and_b32_e32 v48, 0xffff0000, v37
	v_lshlrev_b32_e32 v44, 16, v34
	v_pk_mul_f32 v[34:35], v[106:107], v[104:105]
	v_lshlrev_b32_e32 v20, 16, v228
	v_and_b32_e32 v18, 0xffff0000, v228
	v_mul_f32_e32 v1, v1, v18
	v_lshlrev_b32_e32 v18, 16, v229
	v_mul_f32_e32 v2, v2, v18
	v_and_b32_e32 v18, 0xffff0000, v229
	v_mul_f32_e32 v0, v0, v20
	v_mul_f32_e32 v3, v3, v18
	v_cvt_pk_bf16_f32 v0, v0, v1
	v_cvt_pk_bf16_f32 v1, v2, v3
	v_lshl_add_u64 v[18:19], v[96:97], 0, v[126:127]
	global_store_dwordx2 v[18:19], v[0:1], off offset:64
	v_lshlrev_b32_e32 v96, 16, v84
	v_and_b32_e32 v84, 0xffff0000, v72
	v_and_b32_e32 v72, 0xffff0000, v85
	v_lshlrev_b32_e32 v97, 16, v92
	v_and_b32_e32 v85, 0xffff0000, v88
	v_and_b32_e32 v88, 0xffff0000, v36
	v_lshlrev_b32_e32 v92, 16, v37
	v_and_b32_e32 v37, 0xffff0000, v45
	v_and_b32_e32 v36, 0xffff0000, v33
	v_lshlrev_b32_e32 v33, 16, v50
	v_lshlrev_b32_e32 v45, 16, v46
	v_and_b32_e32 v50, 0xffff0000, v39
	v_and_b32_e32 v39, 0xffff0000, v47
	v_pk_mul_f32 v[136:137], v[90:91], v[88:89]
	v_pk_mul_f32 v[94:95], v[94:95], v[92:93]
	v_pk_mul_f32 v[92:93], v[36:37], v[48:49]
	v_pk_mul_f32 v[90:91], v[44:45], v[32:33]
	v_pk_mul_f32 v[88:89], v[216:217], v[214:215]
	v_pk_mul_f32 v[74:75], v[38:39], v[50:51]
	v_pk_mul_f32 v[50:51], v[198:199], v[200:201]
	v_pk_mul_f32 v[48:49], v[202:203], v[204:205]
	v_pk_mul_f32 v[46:47], v[208:209], v[206:207]
	v_pk_mul_f32 v[44:45], v[210:211], v[212:213]
	v_pk_mul_f32 v[38:39], v[138:139], v[140:141]
	v_pk_mul_f32 v[36:37], v[108:109], v[110:111]
	v_and_b32_e32 v206, 0xffff0000, v68
	v_lshlrev_b32_e32 v207, 16, v69
	v_and_b32_e32 v208, 0xffff0000, v69
	v_lshlrev_b32_e32 v209, 16, v70
	v_and_b32_e32 v210, 0xffff0000, v70
	v_lshlrev_b32_e32 v211, 16, v71
	v_and_b32_e32 v212, 0xffff0000, v71
	v_lshlrev_b32_e32 v213, 16, v64
	v_and_b32_e32 v214, 0xffff0000, v64
	v_lshlrev_b32_e32 v215, 16, v65
	v_and_b32_e32 v216, 0xffff0000, v65
	v_lshlrev_b32_e32 v217, 16, v66
	v_pk_mul_f32 v[32:33], v[100:101], v[102:103]
	v_lshl_add_u64 v[100:101], s[12:13], 0, v[130:131]
	v_lshlrev_b64 v[102:103], 12, v[134:135]
	v_lshl_add_u64 v[100:101], v[100:101], 0, s[16:17]
	v_lshl_add_u64 v[102:103], s[12:13], 0, v[102:103]
	v_lshl_add_u64 v[100:101], v[100:101], 0, v[114:115]
	v_lshl_add_u64 v[102:103], v[102:103], 0, s[16:17]
	v_lshlrev_b32_e32 v0, 16, v230
	v_and_b32_e32 v1, 0xffff0000, v230
	v_lshlrev_b32_e32 v2, 16, v231
	v_and_b32_e32 v3, 0xffff0000, v231
	v_mul_f32_e32 v0, v4, v0
	v_mul_f32_e32 v1, v5, v1
	v_mul_f32_e32 v2, v6, v2
	v_mul_f32_e32 v3, v7, v3
	v_cvt_pk_bf16_f32 v0, v0, v1
	v_cvt_pk_bf16_f32 v1, v2, v3
	v_add_f32_e32 v4, v129, v8
	v_add_f32_e32 v5, v129, v9
	v_add_f32_e32 v6, v129, v10
	v_add_f32_e32 v7, v129, v11
	global_store_dwordx2 v[18:19], v[0:1], off offset:80
	v_add_f32_e32 v10, v129, v13
	v_add_f32_e32 v11, v129, v14
	v_lshlrev_b32_e32 v0, 16, v232
	v_and_b32_e32 v1, 0xffff0000, v232
	v_lshlrev_b32_e32 v2, 16, v233
	v_and_b32_e32 v3, 0xffff0000, v233
	v_mul_f32_e32 v0, v4, v0
	v_mul_f32_e32 v1, v5, v1
	v_mul_f32_e32 v2, v6, v2
	v_mul_f32_e32 v3, v7, v3
	v_cvt_pk_bf16_f32 v0, v0, v1
	v_cvt_pk_bf16_f32 v1, v2, v3
	v_or_b32_e32 v4, s41, v112
	v_mov_b32_e32 v5, v115
	v_lshlrev_b32_e32 v4, 2, v4
	v_lshl_add_u64 v[6:7], s[10:11], 0, v[4:5]
	v_add_f32_e32 v5, v129, v12
	global_store_dwordx2 v[18:19], v[0:1], off offset:96
	v_add_f32_e32 v12, v129, v15
	v_add_co_u32_e32 v8, vcc, s28, v6
	v_ashrrev_i32_e32 v129, 31, v128
	s_nop 0
	v_addc_co_u32_e32 v9, vcc, 0, v7, vcc
	v_lshlrev_b32_e32 v0, 16, v234
	v_and_b32_e32 v1, 0xffff0000, v234
	v_lshlrev_b32_e32 v2, 16, v235
	v_and_b32_e32 v3, 0xffff0000, v235
	v_mul_f32_e32 v0, v5, v0
	v_mul_f32_e32 v1, v10, v1
	v_mul_f32_e32 v2, v11, v2
	v_mul_f32_e32 v3, v12, v3
	v_cvt_pk_bf16_f32 v0, v0, v1
	v_cvt_pk_bf16_f32 v1, v2, v3
	global_store_dwordx2 v[18:19], v[0:1], off offset:112
	global_load_dwordx4 v[0:3], v4, s[10:11] offset:16
	s_nop 0
	global_load_dwordx4 v[12:15], v4, s[10:11]
	global_load_dwordx4 v[20:23], v[8:9], off offset:-4096
	global_load_dwordx4 v[16:19], v[8:9], off
	v_lshl_add_u64 v[4:5], v[6:7], 0, s[18:19]
	v_lshl_add_u64 v[6:7], v[6:7], 0, s[20:21]
	global_load_dwordx4 v[8:11], v[4:5], off offset:16
	s_nop 0
	global_load_dwordx4 v[4:7], v[6:7], off offset:16
	s_waitcnt vmcnt(5)
	v_mov_b32_e32 v104, v0
	s_waitcnt vmcnt(4)
	v_mov_b32_e32 v64, v12
	v_mov_b32_e32 v66, v13
	s_waitcnt vmcnt(2)
	v_mov_b32_e32 v65, v16
	v_mov_b32_e32 v67, v17
	v_mov_b32_e32 v68, v14
	v_mov_b32_e32 v69, v18
	v_mov_b32_e32 v70, v15
	v_mov_b32_e32 v71, v19
	s_waitcnt vmcnt(0)
; __device__ __forceinline__ unsigned pk2(float lo, float hi) { return cvt_pk_bf16(lo, hi); }
; __device__ __forceinline__ void mixer0_phase(KA a, lds8* lds, int tid, int lane, int wave) {
;     ...
;           float z[6][8];
; #pragma unroll
;           for (int i = 0; i < 6; ++i)
; #pragma unroll
;               for (int j = 0; j < 4; ++j) { z[i][2 * j] = bflo(cgv[i][j]) * bflo(xpv[i][j]); z[i][2 * j + 1] = bfhi(cgv[i][j]) * bfhi(xpv[i][j]); }
; #pragma unroll
;           for (int i = 0; i < 4; ++i) { float y[8];
; #pragma unroll
;               for (int j = 0; j < 4; ++j) { y[2 * j] = bflo(bgv[i][j]) * (w0[2 * j] * z[i][2 * j] + w1[2 * j] * z[i + 1][2 * j] + w2[2 * j] * z[i + 2][2 * j]);
;                   y[2 * j + 1] = bfhi(bgv[i][j]) * (w0[2 * j + 1] * z[i][2 * j + 1] + w1[2 * j + 1] * z[i + 1][2 * j + 1] + w2[2 * j + 1] * z[i + 2][2 * j + 1]); }
;               u32x4 o; o.x = pk2(y[0], y[1]); o.y = pk2(y[2], y[3]); o.z = pk2(y[4], y[5]); o.w = pk2(y[6], y[7]);
;               *(u32x4*)(YC + (size_t)(rb + r0 + i) * DM + 1024 + h * 128 + cpc) = o; } }
	v_mov_b32_e32 v105, v4
	v_mov_b32_e32 v106, v1
	v_mov_b32_e32 v107, v5
	v_mov_b32_e32 v108, v2
	v_mov_b32_e32 v109, v6
	v_mov_b32_e32 v110, v3
	v_mov_b32_e32 v111, v7
	v_pk_mul_f32 v[130:131], v[142:143], v[64:65]
	v_pk_mul_f32 v[134:135], v[136:137], v[66:67]
	v_pk_mul_f32 v[138:139], v[94:95], v[68:69]
	v_pk_mul_f32 v[140:141], v[92:93], v[70:71]
	v_pk_mul_f32 v[198:199], v[90:91], v[104:105]
	v_pk_mul_f32 v[200:201], v[88:89], v[106:107]
	v_pk_mul_f32 v[64:65], v[50:51], v[64:65]
	v_pk_mul_f32 v[66:67], v[48:49], v[66:67]
	v_pk_mul_f32 v[68:69], v[46:47], v[68:69]
	v_pk_mul_f32 v[104:105], v[38:39], v[104:105]
	v_pk_mul_f32 v[106:107], v[36:37], v[106:107]
	v_pk_mul_f32 v[202:203], v[86:87], v[108:109]
	v_pk_mul_f32 v[204:205], v[74:75], v[110:111]
	v_pk_mul_f32 v[70:71], v[44:45], v[70:71]
	v_pk_mul_f32 v[108:109], v[34:35], v[108:109]
	v_fma_f32 v50, v50, v20, v130
	v_fma_f32 v64, v143, v20, v64
	v_fma_f32 v48, v48, v21, v134
	v_fma_f32 v66, v137, v21, v66
	v_fma_f32 v46, v46, v22, v138
	v_fma_f32 v68, v95, v22, v68
	v_fma_f32 v44, v44, v23, v140
	v_fma_f32 v38, v38, v8, v198
	v_fma_f32 v74, v91, v8, v104
	v_fma_f32 v36, v36, v9, v200
	v_fma_f32 v86, v89, v9, v106
	v_pk_mul_f32 v[110:111], v[32:33], v[110:111]
	v_fma_f32 v70, v93, v23, v70
	v_fma_f32 v34, v34, v10, v202
	v_fma_f32 v88, v87, v10, v108
	v_fma_f32 v32, v32, v11, v204
	v_add_f32_e32 v50, v50, v131
	v_add_f32_e32 v64, v64, v65
	v_add_f32_e32 v48, v48, v135
	v_add_f32_e32 v65, v66, v67
	v_add_f32_e32 v46, v46, v139
	v_add_f32_e32 v66, v68, v69
	v_add_f32_e32 v44, v44, v141
	v_add_f32_e32 v38, v38, v199
	v_add_f32_e32 v68, v74, v105
	v_add_f32_e32 v36, v36, v201
	v_add_f32_e32 v69, v86, v107
	v_fma_f32 v90, v75, v11, v110
	v_add_f32_e32 v67, v70, v71
	v_add_f32_e32 v34, v34, v203
	v_add_f32_e32 v70, v88, v109
	v_add_f32_e32 v32, v32, v205
	v_mul_f32_e32 v50, v50, v197
	v_mul_f32_e32 v74, v64, v213
	v_mul_f32_e32 v48, v48, v206
	v_mul_f32_e32 v86, v65, v214
	v_mul_f32_e32 v46, v46, v207
	v_mul_f32_e32 v88, v66, v215
	v_mul_f32_e32 v44, v44, v208
	v_mul_f32_e32 v38, v38, v209
	v_mul_f32_e32 v68, v68, v217
	v_mul_f32_e32 v36, v36, v210
	v_mul_f32_e32 v69, v69, v218
	v_cvt_pk_bf16_f32 v64, v50, v48
	v_cvt_pk_bf16_f32 v65, v46, v44
	v_cvt_pk_bf16_f32 v66, v38, v36
	v_add_f32_e32 v71, v90, v111
	v_mul_f32_e32 v90, v67, v216
	v_mul_f32_e32 v34, v34, v211
	v_mul_f32_e32 v32, v32, v212
	v_cvt_pk_bf16_f32 v67, v34, v32
	global_store_dwordx4 v[100:101], v[64:67], off offset:2048
	v_mul_f32_e32 v70, v70, v219
	v_mul_f32_e32 v71, v71, v220
	v_cvt_pk_bf16_f32 v64, v74, v86
	v_cvt_pk_bf16_f32 v65, v88, v90
	v_cvt_pk_bf16_f32 v66, v68, v69
	v_lshl_add_u64 v[68:69], v[102:103], 0, v[114:115]
	v_cvt_pk_bf16_f32 v67, v70, v71
	global_store_dwordx4 v[68:69], v[64:67], off offset:2048
	v_mov_b32_e32 v50, v143
	v_mov_b32_e32 v48, v137
	v_mov_b32_e32 v64, v12
	v_mov_b32_e32 v65, v20
	v_pk_mul_f32 v[64:65], v[50:51], v[64:65]
	v_mov_b32_e32 v46, v95
	v_add_f32_e32 v50, v64, v65
	v_mov_b32_e32 v64, v13
	v_mov_b32_e32 v65, v21
	v_pk_mul_f32 v[64:65], v[48:49], v[64:65]
	v_lshlrev_b32_e32 v70, 16, v54
	v_add_f32_e32 v48, v64, v65
	v_mov_b32_e32 v64, v14
	v_mov_b32_e32 v65, v22
	v_pk_mul_f32 v[64:65], v[46:47], v[64:65]
	v_and_b32_e32 v71, 0xffff0000, v54
	v_add_f32_e32 v46, v64, v65
	v_lshlrev_b32_e32 v74, 16, v55
	v_and_b32_e32 v86, 0xffff0000, v55
	v_pk_mul_f32 v[54:55], v[96:97], v[98:99]
	v_mov_b32_e32 v64, v20
	v_mov_b32_e32 v65, v16
	v_lshlrev_b32_e32 v66, 16, v52
	v_fmac_f32_e32 v50, v54, v16
	v_pk_mul_f32 v[54:55], v[54:55], v[64:65]
	v_mul_f32_e32 v66, v50, v66
	v_fma_f32 v12, v51, v12, v54
	v_pk_mul_f32 v[50:51], v[82:83], v[84:85]
; __device__ __forceinline__ unsigned pk2(float lo, float hi) { return cvt_pk_bf16(lo, hi); }
; __device__ __forceinline__ void mixer0_phase(KA a, lds8* lds, int tid, int lane, int wave) {
;     ...
;               for (int j = 0; j < 4; ++j) { z[i][2 * j] = bflo(cgv[i][j]) * bflo(xpv[i][j]); z[i][2 * j + 1] = bfhi(cgv[i][j]) * bfhi(xpv[i][j]); }
; #pragma unroll
;           for (int i = 0; i < 4; ++i) { float y[8];
; #pragma unroll
;               for (int j = 0; j < 4; ++j) { y[2 * j] = bflo(bgv[i][j]) * (w0[2 * j] * z[i][2 * j] + w1[2 * j] * z[i + 1][2 * j] + w2[2 * j] * z[i + 2][2 * j]);
;                   y[2 * j + 1] = bfhi(bgv[i][j]) * (w0[2 * j + 1] * z[i][2 * j + 1] + w1[2 * j + 1] * z[i + 1][2 * j + 1] + w2[2 * j + 1] * z[i + 2][2 * j + 1]); }
;               u32x4 o; o.x = pk2(y[0], y[1]); o.y = pk2(y[2], y[3]); o.z = pk2(y[4], y[5]); o.w = pk2(y[6], y[7]);
;               *(u32x4*)(YC + (size_t)(rb + r0 + i) * DM + 1024 + h * 128 + cpc) = o; } }
;         __syncthreads();
	v_mov_b32_e32 v16, v21
	v_fmac_f32_e32 v48, v50, v17
	v_pk_mul_f32 v[16:17], v[50:51], v[16:17]
	v_and_b32_e32 v20, 0xffff0000, v40
	v_fma_f32 v13, v49, v13, v16
	v_add_f32_e32 v13, v13, v17
	v_mov_b32_e32 v32, v75
	v_lshlrev_b32_e32 v75, 16, v40
	v_mul_f32_e32 v40, v13, v20
	v_pk_mul_f32 v[16:17], v[80:81], v[78:79]
	v_mov_b32_e32 v20, v22
	v_mov_b32_e32 v21, v18
	v_and_b32_e32 v67, 0xffff0000, v52
	v_lshlrev_b32_e32 v68, 16, v53
	v_and_b32_e32 v69, 0xffff0000, v53
	v_mov_b32_e32 v44, v93
	v_mov_b32_e32 v52, v15
	v_mov_b32_e32 v53, v23
	v_fmac_f32_e32 v46, v16, v18
	v_pk_mul_f32 v[16:17], v[16:17], v[20:21]
	v_pk_mul_f32 v[52:53], v[44:45], v[52:53]
	v_fma_f32 v14, v47, v14, v16
	v_add_f32_e32 v44, v52, v53
	v_add_f32_e32 v14, v14, v17
	v_pk_mul_f32 v[16:17], v[72:73], v[76:77]
	v_mov_b32_e32 v18, v23
	v_mov_b32_e32 v38, v91
	v_mov_b32_e32 v52, v0
	v_mov_b32_e32 v53, v8
	v_fmac_f32_e32 v44, v16, v19
	v_pk_mul_f32 v[16:17], v[16:17], v[18:19]
	v_pk_mul_f32 v[52:53], v[38:39], v[52:53]
	v_lshlrev_b32_e32 v13, 16, v41
	v_fma_f32 v15, v45, v15, v16
	v_add_f32_e32 v38, v52, v53
	v_mov_b32_e32 v36, v89
	v_mov_b32_e32 v52, v1
	v_mov_b32_e32 v53, v9
	v_mul_f32_e32 v20, v14, v13
	v_and_b32_e32 v14, 0xffff0000, v41
	v_add_f32_e32 v15, v15, v17
	v_pk_mul_f32 v[52:53], v[36:37], v[52:53]
	v_mul_f32_e32 v18, v15, v14
	v_pk_mul_f32 v[14:15], v[60:61], v[62:63]
	v_mov_b32_e32 v16, v8
	v_mov_b32_e32 v17, v4
	v_add_f32_e32 v36, v52, v53
	v_fmac_f32_e32 v38, v14, v4
	v_pk_mul_f32 v[14:15], v[14:15], v[16:17]
	v_pk_mul_f32 v[16:17], v[56:57], v[58:59]
	v_add_f32_e32 v12, v12, v55
	v_fmac_f32_e32 v36, v16, v5
	v_mul_f32_e32 v54, v12, v75
	v_mul_f32_e32 v12, v48, v67
	v_mul_f32_e32 v13, v44, v69
	v_mul_f32_e32 v4, v36, v71
	v_cvt_pk_bf16_f32 v12, v66, v12
	v_mul_f32_e32 v46, v46, v68
	v_cvt_pk_bf16_f32 v13, v46, v13
	v_mul_f32_e32 v21, v38, v70
	v_fma_f32 v0, v39, v0, v14
	v_cvt_pk_bf16_f32 v14, v21, v4
	v_mov_b32_e32 v4, v9
	v_pk_mul_f32 v[4:5], v[16:17], v[4:5]
	v_mov_b32_e32 v34, v87
	v_mov_b32_e32 v52, v2
	v_mov_b32_e32 v53, v10
	v_lshlrev_b32_e32 v19, 16, v42
	v_add_f32_e32 v0, v0, v15
	v_fma_f32 v1, v37, v1, v4
	v_pk_mul_f32 v[52:53], v[34:35], v[52:53]
	v_mul_f32_e32 v8, v0, v19
	v_and_b32_e32 v0, 0xffff0000, v42
	v_add_f32_e32 v1, v1, v5
	v_add_f32_e32 v34, v52, v53
	v_mul_f32_e32 v9, v1, v0
	v_pk_mul_f32 v[0:1], v[30:31], v[28:29]
	v_mov_b32_e32 v4, v10
	v_mov_b32_e32 v5, v6
	v_fmac_f32_e32 v34, v0, v6
	v_pk_mul_f32 v[0:1], v[0:1], v[4:5]
	v_mov_b32_e32 v52, v3
	v_mov_b32_e32 v53, v11
	v_fma_f32 v0, v35, v2, v0
	v_pk_mul_f32 v[52:53], v[32:33], v[52:53]
	v_lshlrev_b32_e32 v15, 16, v43
	v_add_f32_e32 v0, v0, v1
	v_add_f32_e32 v32, v52, v53
	v_mul_f32_e32 v4, v0, v15
	v_pk_mul_f32 v[0:1], v[24:25], v[26:27]
	v_mov_b32_e32 v6, v11
	v_lshlrev_b64 v[52:53], 12, v[132:133]
	v_fmac_f32_e32 v32, v0, v7
	v_pk_mul_f32 v[0:1], v[0:1], v[6:7]
	v_lshl_add_u64 v[52:53], s[12:13], 0, v[52:53]
	v_fma_f32 v0, v33, v3, v0
	v_lshl_add_u64 v[52:53], v[52:53], 0, s[16:17]
	v_and_b32_e32 v2, 0xffff0000, v43
	v_add_f32_e32 v0, v0, v1
	v_lshl_add_u64 v[52:53], v[52:53], 0, v[114:115]
	v_mul_f32_e32 v5, v32, v86
	v_mul_f32_e32 v3, v0, v2
	v_mul_f32_e32 v16, v34, v74
	v_cvt_pk_bf16_f32 v15, v16, v5
	global_store_dwordx4 v[52:53], v[12:15], off offset:2048
	v_cvt_pk_bf16_f32 v0, v54, v40
	v_cvt_pk_bf16_f32 v1, v20, v18
	v_cvt_pk_bf16_f32 v2, v8, v9
	v_cvt_pk_bf16_f32 v3, v4, v3
	v_lshlrev_b64 v[4:5], 12, v[128:129]
	v_lshl_add_u64 v[4:5], s[12:13], 0, v[4:5]
	v_lshl_add_u64 v[4:5], v[4:5], 0, s[16:17]
	v_lshl_add_u64 v[4:5], v[4:5], 0, v[114:115]
	global_store_dwordx4 v[4:5], v[0:3], off offset:2048
	s_barrier
	s_cbranch_scc0 .LBB0_499
